# hy_conv_sub: Toeplitz filter table built by hand (9 batched loads per thread written to the 8 shifted rows, no per-element division or serialized load/wait)
# speedup vs baseline: 1.0804x; 1.0091x over previous
; __device__ __forceinline__ int opaque_tid() { int t = threadIdx.x; asm volatile("" : "+v"(t)); return t; }
; __device__ __forceinline__ bf16_t f2bf(float f) { return (bf16_t)(pack2(f, 0.f) & 0xffffu); }
; __device__ void hy_conv_sub(unsigned char* lds, const Params& p, int l, int c, int L, int posoff) {
;   bf16_t* cp = (bf16_t*)lds;
;   bf16_t* uL = cp + 8 * HY_CL;
;   const int tid = opaque_tid(), lane = tid & 63, w = tid >> 6, lr = lane & 15, lg = lane >> 4;
;   const float* hf = (const float*)(p.ws + OFF_FILT) + ((size_t)(l * 256 + c) * 2 + 0) * LTOT + posoff;
;   const float* hb = hf + LTOT;
;   const bf16_t* uT = (const bf16_t*)(p.ws + OFF_ACT);
;   bf16_t* ycv = (bf16_t*)(p.ws + OFF_YCV);
; #pragma unroll 8
;   for (int idx = tid; idx < 8 * HY_CL; idx += 512) {
;     const int cc = idx / HY_CL, m = idx - cc * HY_CL;
;     const int n = m - cc - HY_OFF;
;     const int a = n <= 0 ? -n : n;
;     const int ac = a < L ? a : L - 1;
;     const float* base = (n <= 0) ? hf : hb;
;     const float v = base[ac];
;     cp[idx] = f2bf(a < L ? v : 0.f);
;   }
.LBB0_414:
	v_mov_b32_e32 v0, v195
	s_add_i32 s8, s6, s22
	s_mov_b32 s0, 0x8100
	s_ashr_i32 s9, s8, 31
	s_movk_i32 s4, 0x800
	s_mov_b64 s[12:13], exec
	s_mul_i32 s1, s8, 0x4800
	v_readlane_b32 s2, v251, 18
	s_mul_hi_i32 s0, s8, 0x4800
	v_readlane_b32 s3, v251, 19
	s_add_u32 s14, s2, s1
	s_addc_u32 s15, s3, s0
	v_add_u32_e32 v28, 0xfffff7e9, v0
	v_sub_u32_e32 v29, 0, v28
	v_max_i32_e32 v19, v28, v29
	v_cmp_lt_i32_e32 vcc, 0, v28
	v_min_i32_e32 v29, 0x7ff, v19
	v_lshlrev_b32_e32 v29, 2, v29
	v_cndmask_b32_e32 v30, 0, v238, vcc
	v_add_u32_e32 v1, v29, v30
	global_load_dword v10, v1, s[14:15]
	v_add_u32_e32 v28, 0xfffff9e9, v0
	v_sub_u32_e32 v29, 0, v28
	v_max_i32_e32 v20, v28, v29
	v_cmp_lt_i32_e32 vcc, 0, v28
	v_min_i32_e32 v29, 0x7ff, v20
	v_lshlrev_b32_e32 v29, 2, v29
	v_cndmask_b32_e32 v30, 0, v238, vcc
	v_add_u32_e32 v2, v29, v30
	global_load_dword v11, v2, s[14:15]
	v_add_u32_e32 v28, 0xfffffbe9, v0
	v_sub_u32_e32 v29, 0, v28
	v_max_i32_e32 v21, v28, v29
	v_cmp_lt_i32_e32 vcc, 0, v28
	v_min_i32_e32 v29, 0x7ff, v21
	v_lshlrev_b32_e32 v29, 2, v29
	v_cndmask_b32_e32 v30, 0, v238, vcc
	v_add_u32_e32 v3, v29, v30
	global_load_dword v12, v3, s[14:15]
	v_add_u32_e32 v28, 0xfffffde9, v0
	v_sub_u32_e32 v29, 0, v28
	v_max_i32_e32 v22, v28, v29
	v_cmp_lt_i32_e32 vcc, 0, v28
	v_min_i32_e32 v29, 0x7ff, v22
	v_lshlrev_b32_e32 v29, 2, v29
	v_cndmask_b32_e32 v30, 0, v238, vcc
	v_add_u32_e32 v4, v29, v30
	global_load_dword v13, v4, s[14:15]
	v_add_u32_e32 v28, 0xffffffe9, v0
	v_sub_u32_e32 v29, 0, v28
	v_max_i32_e32 v23, v28, v29
	v_cmp_lt_i32_e32 vcc, 0, v28
	v_min_i32_e32 v29, 0x7ff, v23
	v_lshlrev_b32_e32 v29, 2, v29
	v_cndmask_b32_e32 v30, 0, v238, vcc
	v_add_u32_e32 v5, v29, v30
	global_load_dword v14, v5, s[14:15]
	v_add_u32_e32 v28, 0x1e9, v0
	v_sub_u32_e32 v29, 0, v28
	v_max_i32_e32 v24, v28, v29
	v_cmp_lt_i32_e32 vcc, 0, v28
	v_min_i32_e32 v29, 0x7ff, v24
	v_lshlrev_b32_e32 v29, 2, v29
	v_cndmask_b32_e32 v30, 0, v238, vcc
	v_add_u32_e32 v6, v29, v30
	global_load_dword v15, v6, s[14:15]
	v_add_u32_e32 v28, 0x3e9, v0
	v_sub_u32_e32 v29, 0, v28
	v_max_i32_e32 v25, v28, v29
	v_cmp_lt_i32_e32 vcc, 0, v28
	v_min_i32_e32 v29, 0x7ff, v25
	v_lshlrev_b32_e32 v29, 2, v29
	v_cndmask_b32_e32 v30, 0, v238, vcc
	v_add_u32_e32 v7, v29, v30
	global_load_dword v16, v7, s[14:15]
	v_add_u32_e32 v28, 0x5e9, v0
	v_sub_u32_e32 v29, 0, v28
	v_max_i32_e32 v26, v28, v29
	v_cmp_lt_i32_e32 vcc, 0, v28
	v_min_i32_e32 v29, 0x7ff, v26
	v_lshlrev_b32_e32 v29, 2, v29
	v_cndmask_b32_e32 v30, 0, v238, vcc
	v_add_u32_e32 v8, v29, v30
	global_load_dword v17, v8, s[14:15]
	v_add_u32_e32 v28, 0x7e9, v0
	v_sub_u32_e32 v29, 0, v28
	v_max_i32_e32 v27, v28, v29
	v_cmp_lt_i32_e32 vcc, 0, v28
	v_min_i32_e32 v29, 0x7ff, v27
	v_lshlrev_b32_e32 v29, 2, v29
	v_cndmask_b32_e32 v30, 0, v238, vcc
	v_add_u32_e32 v9, v29, v30
	global_load_dword v18, v9, s[14:15]
	v_lshlrev_b32_e32 v31, 1, v0
	v_add_u32_e32 v32, -14, v31
	v_add_u32_e32 v33, 0x1ff2, v31
	s_waitcnt vmcnt(7)
	v_cmp_gt_i32_e32 vcc, 0x800, v20
	v_cvt_pk_bf16_f32 v11, v11, v11
	s_nop 0
	v_cndmask_b32_e32 v11, 0, v11, vcc
	ds_write_b16 v31, v11 offset:1010
	ds_write_b16 v31, v11 offset:9268
	ds_write_b16 v31, v11 offset:17526
	ds_write_b16 v31, v11 offset:25784
	ds_write_b16 v31, v11 offset:34042
	ds_write_b16 v31, v11 offset:42300
	ds_write_b16 v31, v11 offset:50558
	ds_write_b16 v31, v11 offset:58816
	s_waitcnt vmcnt(6)
	v_cmp_gt_i32_e32 vcc, 0x800, v21
	v_cvt_pk_bf16_f32 v12, v12, v12
	s_nop 0
	v_cndmask_b32_e32 v12, 0, v12, vcc
	ds_write_b16 v31, v12 offset:2034
	ds_write_b16 v31, v12 offset:10292
	ds_write_b16 v31, v12 offset:18550
	ds_write_b16 v31, v12 offset:26808
	ds_write_b16 v31, v12 offset:35066
	ds_write_b16 v31, v12 offset:43324
	ds_write_b16 v31, v12 offset:51582
	ds_write_b16 v31, v12 offset:59840
	s_waitcnt vmcnt(5)
; __device__ __forceinline__ bf16_t f2bf(float f) { return (bf16_t)(pack2(f, 0.f) & 0xffffu); }
; __device__ void hy_conv_sub(unsigned char* lds, const Params& p, int l, int c, int L, int posoff) {
;     ...
; #pragma unroll 8
;   for (int idx = tid; idx < 8 * HY_CL; idx += 512) {
;     const int cc = idx / HY_CL, m = idx - cc * HY_CL;
;     const int n = m - cc - HY_OFF;
;     const int a = n <= 0 ? -n : n;
;     const int ac = a < L ? a : L - 1;
;     const float* base = (n <= 0) ? hf : hb;
;     const float v = base[ac];
;     cp[idx] = f2bf(a < L ? v : 0.f);
;   }
;   for (int idx = tid; idx < 8 * (L >> 3); idx += 512) {
;     const int bb = idx / (L >> 3), q = idx - bb * (L >> 3);
;     *(uint4*)(uL + bb * 2048 + q * 8) = *(const uint4*)(uT + ((size_t)c * 8 + bb) * LTOT + posoff + q * 8);
;   }
	v_cmp_gt_i32_e32 vcc, 0x800, v22
	v_cvt_pk_bf16_f32 v13, v13, v13
	s_nop 0
	v_cndmask_b32_e32 v13, 0, v13, vcc
	ds_write_b16 v31, v13 offset:3058
	ds_write_b16 v31, v13 offset:11316
	ds_write_b16 v31, v13 offset:19574
	ds_write_b16 v31, v13 offset:27832
	ds_write_b16 v31, v13 offset:36090
	ds_write_b16 v31, v13 offset:44348
	ds_write_b16 v31, v13 offset:52606
	ds_write_b16 v31, v13 offset:60864
	s_waitcnt vmcnt(4)
	v_cmp_gt_i32_e32 vcc, 0x800, v23
	v_cvt_pk_bf16_f32 v14, v14, v14
	s_nop 0
	v_cndmask_b32_e32 v14, 0, v14, vcc
	ds_write_b16 v31, v14 offset:4082
	ds_write_b16 v31, v14 offset:12340
	ds_write_b16 v31, v14 offset:20598
	ds_write_b16 v31, v14 offset:28856
	ds_write_b16 v31, v14 offset:37114
	ds_write_b16 v31, v14 offset:45372
	ds_write_b16 v31, v14 offset:53630
	ds_write_b16 v31, v14 offset:61888
	s_waitcnt vmcnt(3)
	v_cmp_gt_i32_e32 vcc, 0x800, v24
	v_cvt_pk_bf16_f32 v15, v15, v15
	s_nop 0
	v_cndmask_b32_e32 v15, 0, v15, vcc
	ds_write_b16 v31, v15 offset:5106
	ds_write_b16 v31, v15 offset:13364
	ds_write_b16 v31, v15 offset:21622
	ds_write_b16 v31, v15 offset:29880
	ds_write_b16 v31, v15 offset:38138
	ds_write_b16 v31, v15 offset:46396
	ds_write_b16 v31, v15 offset:54654
	ds_write_b16 v31, v15 offset:62912
	s_waitcnt vmcnt(2)
	v_cmp_gt_i32_e32 vcc, 0x800, v25
	v_cvt_pk_bf16_f32 v16, v16, v16
	s_nop 0
	v_cndmask_b32_e32 v16, 0, v16, vcc
	ds_write_b16 v31, v16 offset:6130
	ds_write_b16 v31, v16 offset:14388
	ds_write_b16 v31, v16 offset:22646
	ds_write_b16 v31, v16 offset:30904
	ds_write_b16 v31, v16 offset:39162
	ds_write_b16 v31, v16 offset:47420
	ds_write_b16 v31, v16 offset:55678
	ds_write_b16 v31, v16 offset:63936
	s_waitcnt vmcnt(1)
	v_cmp_gt_i32_e32 vcc, 0x800, v26
	v_cvt_pk_bf16_f32 v17, v17, v17
	s_nop 0
	v_cndmask_b32_e32 v17, 0, v17, vcc
	ds_write_b16 v31, v17 offset:7154
	ds_write_b16 v31, v17 offset:15412
	ds_write_b16 v31, v17 offset:23670
	ds_write_b16 v31, v17 offset:31928
	ds_write_b16 v31, v17 offset:40186
	ds_write_b16 v31, v17 offset:48444
	ds_write_b16 v31, v17 offset:56702
	ds_write_b16 v31, v17 offset:64960
	s_waitcnt vmcnt(8)
	v_cmp_gt_i32_e32 vcc, 0x800, v19
	v_cvt_pk_bf16_f32 v10, v10, v10
	s_nop 0
	v_cndmask_b32_e32 v10, 0, v10, vcc
	ds_write_b16 v31, v10 offset:57792
	v_cmp_le_u32_e32 vcc, 1, v0
	s_and_b64 exec, exec, vcc
	ds_write_b16 v31, v10 offset:49534
	v_cmp_le_u32_e32 vcc, 2, v0
	s_and_b64 exec, exec, vcc
	ds_write_b16 v31, v10 offset:41276
	v_cmp_le_u32_e32 vcc, 3, v0
	s_and_b64 exec, exec, vcc
	ds_write_b16 v31, v10 offset:33018
	v_cmp_le_u32_e32 vcc, 4, v0
	s_and_b64 exec, exec, vcc
	ds_write_b16 v31, v10 offset:24760
	v_cmp_le_u32_e32 vcc, 5, v0
	s_and_b64 exec, exec, vcc
	ds_write_b16 v31, v10 offset:16502
	v_cmp_le_u32_e32 vcc, 6, v0
	s_and_b64 exec, exec, vcc
	ds_write_b16 v31, v10 offset:8244
	v_cmp_le_u32_e32 vcc, 7, v0
	s_and_b64 exec, exec, vcc
	ds_write_b16 v32, v10
	s_mov_b64 exec, s[12:13]
	s_waitcnt vmcnt(0)
	v_cmp_gt_i32_e32 vcc, 0x800, v27
	v_cvt_pk_bf16_f32 v18, v18, v18
	s_nop 0
	v_cndmask_b32_e32 v18, 0, v18, vcc
	v_cmp_ge_u32_e32 vcc, 38, v0
	s_and_b64 exec, exec, vcc
	ds_write_b16 v33, v18
	v_cmp_ge_u32_e32 vcc, 37, v0
	s_and_b64 exec, exec, vcc
	ds_write_b16 v33, v18 offset:8258
	v_cmp_ge_u32_e32 vcc, 36, v0
	s_and_b64 exec, exec, vcc
	ds_write_b16 v33, v18 offset:16516
	v_cmp_ge_u32_e32 vcc, 35, v0
	s_and_b64 exec, exec, vcc
	ds_write_b16 v33, v18 offset:24774
	v_cmp_ge_u32_e32 vcc, 34, v0
	s_and_b64 exec, exec, vcc
	ds_write_b16 v33, v18 offset:33032
	v_cmp_ge_u32_e32 vcc, 33, v0
	s_and_b64 exec, exec, vcc
	ds_write_b16 v33, v18 offset:41290
	v_cmp_ge_u32_e32 vcc, 32, v0
	s_and_b64 exec, exec, vcc
	ds_write_b16 v33, v18 offset:49548
	v_cmp_ge_u32_e32 vcc, 31, v0
	s_and_b64 exec, exec, vcc
	ds_write_b16 v33, v18 offset:57806
	s_mov_b64 exec, s[12:13]
	v_cmp_gt_i32_e32 vcc, s4, v0
	s_and_saveexec_b64 s[0:1], vcc
	v_readlane_b32 s14, v251, 31
	v_readlane_b32 s15, v251, 32
	s_movk_i32 s16, 0x1200
	s_cbranch_execz .LBB0_437
	s_ashr_i32 s7, s6, 31
	v_readlane_b32 s4, v253, 39
	s_lshl_b64 s[2:3], s[6:7], 3
	v_lshlrev_b32_e32 v1, 3, v0
	v_lshl_add_u32 v2, v0, 4, s4
	s_mov_b64 s[4:5], 0
	v_mov_b32_e32 v3, v0

; __device__ __forceinline__ int opaque_tid() { int t = threadIdx.x; asm volatile("" : "+v"(t)); return t; }
; __device__ __forceinline__ bf16_t f2bf(float f) { return (bf16_t)(pack2(f, 0.f) & 0xffffu); }
; __device__ void hy_conv_sub(unsigned char* lds, const Params& p, int l, int c, int L, int posoff) {
;   bf16_t* cp = (bf16_t*)lds;
;   bf16_t* uL = cp + 8 * HY_CL;
;   const int tid = opaque_tid(), lane = tid & 63, w = tid >> 6, lr = lane & 15, lg = lane >> 4;
;   const float* hf = (const float*)(p.ws + OFF_FILT) + ((size_t)(l * 256 + c) * 2 + 0) * LTOT + posoff;
;   const float* hb = hf + LTOT;
;   const bf16_t* uT = (const bf16_t*)(p.ws + OFF_ACT);
;   bf16_t* ycv = (bf16_t*)(p.ws + OFF_YCV);
; #pragma unroll 8
;   for (int idx = tid; idx < 8 * HY_CL; idx += 512) {
;     const int cc = idx / HY_CL, m = idx - cc * HY_CL;
;     const int n = m - cc - HY_OFF;
;     const int a = n <= 0 ? -n : n;
;     const int ac = a < L ? a : L - 1;
;     const float* base = (n <= 0) ? hf : hb;
;     const float v = base[ac];
;     cp[idx] = f2bf(a < L ? v : 0.f);
;   }
; __global__ void __launch_bounds__(512) fwd_kernel(Params p) {
;     ...
;       if (need_ctx) hy_conv_sub(lds, p, l, c, 256, 2048);
.LBB0_444:
	s_or_b64 exec, exec, s[2:3]
	s_and_b64 vcc, exec, s[38:39]
	s_barrier
	s_cbranch_vccnz .LBB0_413
	v_mov_b32_e32 v0, v195
	s_mov_b32 s0, 0x8100
	s_ashr_i32 s7, s6, 31
	s_movk_i32 s4, 0x100
	s_movk_i32 s20, 0xe00
	s_mov_b64 s[8:9], exec
	s_mul_i32 s1, s6, 0x4800
	v_readlane_b32 s2, v251, 18
	s_mul_hi_i32 s0, s6, 0x4800
	v_readlane_b32 s3, v251, 19
	s_add_u32 s1, s2, s1
	s_addc_u32 s0, s3, s0
	s_add_u32 s12, s1, 0x2000
	s_addc_u32 s13, s0, 0
	v_add_u32_e32 v28, 0xfffff7e9, v0
	v_sub_u32_e32 v29, 0, v28
	v_max_i32_e32 v19, v28, v29
	v_cmp_lt_i32_e32 vcc, 0, v28
	v_min_i32_e32 v29, 0xff, v19
	v_lshlrev_b32_e32 v29, 2, v29
	v_cndmask_b32_e32 v30, 0, v238, vcc
	v_add_u32_e32 v1, v29, v30
	global_load_dword v10, v1, s[12:13]
	v_add_u32_e32 v28, 0xfffff9e9, v0
	v_sub_u32_e32 v29, 0, v28
	v_max_i32_e32 v20, v28, v29
	v_cmp_lt_i32_e32 vcc, 0, v28
	v_min_i32_e32 v29, 0xff, v20
	v_lshlrev_b32_e32 v29, 2, v29
	v_cndmask_b32_e32 v30, 0, v238, vcc
	v_add_u32_e32 v2, v29, v30
	global_load_dword v11, v2, s[12:13]
	v_add_u32_e32 v28, 0xfffffbe9, v0
	v_sub_u32_e32 v29, 0, v28
	v_max_i32_e32 v21, v28, v29
	v_cmp_lt_i32_e32 vcc, 0, v28
	v_min_i32_e32 v29, 0xff, v21
	v_lshlrev_b32_e32 v29, 2, v29
	v_cndmask_b32_e32 v30, 0, v238, vcc
	v_add_u32_e32 v3, v29, v30
	global_load_dword v12, v3, s[12:13]
	v_add_u32_e32 v28, 0xfffffde9, v0
	v_sub_u32_e32 v29, 0, v28
	v_max_i32_e32 v22, v28, v29
	v_cmp_lt_i32_e32 vcc, 0, v28
	v_min_i32_e32 v29, 0xff, v22
	v_lshlrev_b32_e32 v29, 2, v29
	v_cndmask_b32_e32 v30, 0, v238, vcc
	v_add_u32_e32 v4, v29, v30
	global_load_dword v13, v4, s[12:13]
	v_add_u32_e32 v28, 0xffffffe9, v0
	v_sub_u32_e32 v29, 0, v28
	v_max_i32_e32 v23, v28, v29
	v_cmp_lt_i32_e32 vcc, 0, v28
	v_min_i32_e32 v29, 0xff, v23
	v_lshlrev_b32_e32 v29, 2, v29
	v_cndmask_b32_e32 v30, 0, v238, vcc
	v_add_u32_e32 v5, v29, v30
	global_load_dword v14, v5, s[12:13]
	v_add_u32_e32 v28, 0x1e9, v0
	v_sub_u32_e32 v29, 0, v28
	v_max_i32_e32 v24, v28, v29
	v_cmp_lt_i32_e32 vcc, 0, v28
	v_min_i32_e32 v29, 0xff, v24
	v_lshlrev_b32_e32 v29, 2, v29
	v_cndmask_b32_e32 v30, 0, v238, vcc
	v_add_u32_e32 v6, v29, v30
	global_load_dword v15, v6, s[12:13]
	v_add_u32_e32 v28, 0x3e9, v0
	v_sub_u32_e32 v29, 0, v28
	v_max_i32_e32 v25, v28, v29
	v_cmp_lt_i32_e32 vcc, 0, v28
	v_min_i32_e32 v29, 0xff, v25
	v_lshlrev_b32_e32 v29, 2, v29
	v_cndmask_b32_e32 v30, 0, v238, vcc
	v_add_u32_e32 v7, v29, v30
	global_load_dword v16, v7, s[12:13]
	v_add_u32_e32 v28, 0x5e9, v0
	v_sub_u32_e32 v29, 0, v28
	v_max_i32_e32 v26, v28, v29
	v_cmp_lt_i32_e32 vcc, 0, v28
	v_min_i32_e32 v29, 0xff, v26
	v_lshlrev_b32_e32 v29, 2, v29
	v_cndmask_b32_e32 v30, 0, v238, vcc
	v_add_u32_e32 v8, v29, v30
	global_load_dword v17, v8, s[12:13]
	v_add_u32_e32 v28, 0x7e9, v0
	v_sub_u32_e32 v29, 0, v28
	v_max_i32_e32 v27, v28, v29
	v_cmp_lt_i32_e32 vcc, 0, v28
	v_min_i32_e32 v29, 0xff, v27
	v_lshlrev_b32_e32 v29, 2, v29
	v_cndmask_b32_e32 v30, 0, v238, vcc
	v_add_u32_e32 v9, v29, v30
	global_load_dword v18, v9, s[12:13]
	v_lshlrev_b32_e32 v31, 1, v0
	v_add_u32_e32 v32, -14, v31
	v_add_u32_e32 v33, 0x1ff2, v31
	s_waitcnt vmcnt(7)
	v_cmp_gt_i32_e32 vcc, 0x100, v20
	v_cvt_pk_bf16_f32 v11, v11, v11
	s_nop 0
	v_cndmask_b32_e32 v11, 0, v11, vcc
	ds_write_b16 v31, v11 offset:1010
	ds_write_b16 v31, v11 offset:9268
	ds_write_b16 v31, v11 offset:17526
	ds_write_b16 v31, v11 offset:25784
	ds_write_b16 v31, v11 offset:34042
	ds_write_b16 v31, v11 offset:42300
	ds_write_b16 v31, v11 offset:50558
	ds_write_b16 v31, v11 offset:58816
	s_waitcnt vmcnt(6)
	v_cmp_gt_i32_e32 vcc, 0x100, v21
	v_cvt_pk_bf16_f32 v12, v12, v12
	s_nop 0
	v_cndmask_b32_e32 v12, 0, v12, vcc
	ds_write_b16 v31, v12 offset:2034
	ds_write_b16 v31, v12 offset:10292
	ds_write_b16 v31, v12 offset:18550
	ds_write_b16 v31, v12 offset:26808
	ds_write_b16 v31, v12 offset:35066
	ds_write_b16 v31, v12 offset:43324
	ds_write_b16 v31, v12 offset:51582
	ds_write_b16 v31, v12 offset:59840
	s_waitcnt vmcnt(5)
; __device__ __forceinline__ bf16_t f2bf(float f) { return (bf16_t)(pack2(f, 0.f) & 0xffffu); }
; __device__ void hy_conv_sub(unsigned char* lds, const Params& p, int l, int c, int L, int posoff) {
;     ...
; #pragma unroll 8
;   for (int idx = tid; idx < 8 * HY_CL; idx += 512) {
;     const int cc = idx / HY_CL, m = idx - cc * HY_CL;
;     const int n = m - cc - HY_OFF;
;     const int a = n <= 0 ? -n : n;
;     const int ac = a < L ? a : L - 1;
;     const float* base = (n <= 0) ? hf : hb;
;     const float v = base[ac];
;     cp[idx] = f2bf(a < L ? v : 0.f);
;   }
;   for (int idx = tid; idx < 8 * (L >> 3); idx += 512) {
;     const int bb = idx / (L >> 3), q = idx - bb * (L >> 3);
;     *(uint4*)(uL + bb * 2048 + q * 8) = *(const uint4*)(uT + ((size_t)c * 8 + bb) * LTOT + posoff + q * 8);
;   }
	v_cmp_gt_i32_e32 vcc, 0x100, v22
	v_cvt_pk_bf16_f32 v13, v13, v13
	s_nop 0
	v_cndmask_b32_e32 v13, 0, v13, vcc
	ds_write_b16 v31, v13 offset:3058
	ds_write_b16 v31, v13 offset:11316
	ds_write_b16 v31, v13 offset:19574
	ds_write_b16 v31, v13 offset:27832
	ds_write_b16 v31, v13 offset:36090
	ds_write_b16 v31, v13 offset:44348
	ds_write_b16 v31, v13 offset:52606
	ds_write_b16 v31, v13 offset:60864
	s_waitcnt vmcnt(4)
	v_cmp_gt_i32_e32 vcc, 0x100, v23
	v_cvt_pk_bf16_f32 v14, v14, v14
	s_nop 0
	v_cndmask_b32_e32 v14, 0, v14, vcc
	ds_write_b16 v31, v14 offset:4082
	ds_write_b16 v31, v14 offset:12340
	ds_write_b16 v31, v14 offset:20598
	ds_write_b16 v31, v14 offset:28856
	ds_write_b16 v31, v14 offset:37114
	ds_write_b16 v31, v14 offset:45372
	ds_write_b16 v31, v14 offset:53630
	ds_write_b16 v31, v14 offset:61888
	s_waitcnt vmcnt(3)
	v_cmp_gt_i32_e32 vcc, 0x100, v24
	v_cvt_pk_bf16_f32 v15, v15, v15
	s_nop 0
	v_cndmask_b32_e32 v15, 0, v15, vcc
	ds_write_b16 v31, v15 offset:5106
	ds_write_b16 v31, v15 offset:13364
	ds_write_b16 v31, v15 offset:21622
	ds_write_b16 v31, v15 offset:29880
	ds_write_b16 v31, v15 offset:38138
	ds_write_b16 v31, v15 offset:46396
	ds_write_b16 v31, v15 offset:54654
	ds_write_b16 v31, v15 offset:62912
	s_waitcnt vmcnt(2)
	v_cmp_gt_i32_e32 vcc, 0x100, v25
	v_cvt_pk_bf16_f32 v16, v16, v16
	s_nop 0
	v_cndmask_b32_e32 v16, 0, v16, vcc
	ds_write_b16 v31, v16 offset:6130
	ds_write_b16 v31, v16 offset:14388
	ds_write_b16 v31, v16 offset:22646
	ds_write_b16 v31, v16 offset:30904
	ds_write_b16 v31, v16 offset:39162
	ds_write_b16 v31, v16 offset:47420
	ds_write_b16 v31, v16 offset:55678
	ds_write_b16 v31, v16 offset:63936
	s_waitcnt vmcnt(1)
	v_cmp_gt_i32_e32 vcc, 0x100, v26
	v_cvt_pk_bf16_f32 v17, v17, v17
	s_nop 0
	v_cndmask_b32_e32 v17, 0, v17, vcc
	ds_write_b16 v31, v17 offset:7154
	ds_write_b16 v31, v17 offset:15412
	ds_write_b16 v31, v17 offset:23670
	ds_write_b16 v31, v17 offset:31928
	ds_write_b16 v31, v17 offset:40186
	ds_write_b16 v31, v17 offset:48444
	ds_write_b16 v31, v17 offset:56702
	ds_write_b16 v31, v17 offset:64960
	s_waitcnt vmcnt(8)
	v_cmp_gt_i32_e32 vcc, 0x100, v19
	v_cvt_pk_bf16_f32 v10, v10, v10
	s_nop 0
	v_cndmask_b32_e32 v10, 0, v10, vcc
	ds_write_b16 v31, v10 offset:57792
	v_cmp_le_u32_e32 vcc, 1, v0
	s_and_b64 exec, exec, vcc
	ds_write_b16 v31, v10 offset:49534
	v_cmp_le_u32_e32 vcc, 2, v0
	s_and_b64 exec, exec, vcc
	ds_write_b16 v31, v10 offset:41276
	v_cmp_le_u32_e32 vcc, 3, v0
	s_and_b64 exec, exec, vcc
	ds_write_b16 v31, v10 offset:33018
	v_cmp_le_u32_e32 vcc, 4, v0
	s_and_b64 exec, exec, vcc
	ds_write_b16 v31, v10 offset:24760
	v_cmp_le_u32_e32 vcc, 5, v0
	s_and_b64 exec, exec, vcc
	ds_write_b16 v31, v10 offset:16502
	v_cmp_le_u32_e32 vcc, 6, v0
	s_and_b64 exec, exec, vcc
	ds_write_b16 v31, v10 offset:8244
	v_cmp_le_u32_e32 vcc, 7, v0
	s_and_b64 exec, exec, vcc
	ds_write_b16 v32, v10
	s_mov_b64 exec, s[8:9]
	s_waitcnt vmcnt(0)
	v_cmp_gt_i32_e32 vcc, 0x100, v27
	v_cvt_pk_bf16_f32 v18, v18, v18
	s_nop 0
	v_cndmask_b32_e32 v18, 0, v18, vcc
	v_cmp_ge_u32_e32 vcc, 38, v0
	s_and_b64 exec, exec, vcc
	ds_write_b16 v33, v18
	v_cmp_ge_u32_e32 vcc, 37, v0
	s_and_b64 exec, exec, vcc
	ds_write_b16 v33, v18 offset:8258
	v_cmp_ge_u32_e32 vcc, 36, v0
	s_and_b64 exec, exec, vcc
	ds_write_b16 v33, v18 offset:16516
	v_cmp_ge_u32_e32 vcc, 35, v0
	s_and_b64 exec, exec, vcc
	ds_write_b16 v33, v18 offset:24774
	v_cmp_ge_u32_e32 vcc, 34, v0
	s_and_b64 exec, exec, vcc
	ds_write_b16 v33, v18 offset:33032
	v_cmp_ge_u32_e32 vcc, 33, v0
	s_and_b64 exec, exec, vcc
	ds_write_b16 v33, v18 offset:41290
	v_cmp_ge_u32_e32 vcc, 32, v0
	s_and_b64 exec, exec, vcc
	ds_write_b16 v33, v18 offset:49548
	v_cmp_ge_u32_e32 vcc, 31, v0
	s_and_b64 exec, exec, vcc
	ds_write_b16 v33, v18 offset:57806
	s_mov_b64 exec, s[8:9]
	v_cmp_gt_i32_e32 vcc, s4, v0
	s_and_saveexec_b64 s[0:1], vcc
	v_readlane_b32 s12, v252, 5
	v_readlane_b32 s13, v252, 6
	s_movk_i32 s14, 0x1200
	s_cbranch_execz .LBB0_468
	v_readlane_b32 s4, v253, 39
	s_lshl_b64 s[2:3], s[6:7], 3
	v_lshlrev_b32_e32 v1, 3, v0
	v_lshl_add_u32 v2, v0, 4, s4
	s_mov_b64 s[4:5], 0
	v_mov_b32_e32 v3, v0
